# P2 GEMM prologue: both pipeline-fill LDS-DMA batches issued together
# baseline (speedup 1.0000x reference)
; __device__ __forceinline__ int fresh_tid() { int t = threadIdx.x; asm volatile("" : "+v"(t)); return t; }
; #define PG8_STAGE(bufoff, gbase) PG8_STAGE_(bufoff, gbase, voffA)
; #define PG8_STAGEB(bufoff, gbase) PG8_STAGE_(bufoff, gbase, voffB)
; #define PG8_WAIT_V(n) asm volatile("s_waitcnt vmcnt(" #n ")" ::: "memory")
; #define PG8_BAR __builtin_amdgcn_s_barrier()
; template <class Epi>
; __device__ __forceinline__ void gemm_phase(LAS unsigned char* lds, const Gemm g, const StaticOrder& S, const Epi& E) {
;     const int tid = fresh_tid(), wid = __builtin_amdgcn_readfirstlane(tid >> 6), lane = tid & 63, wr = wid >> 2, wc = wid & 3, fr = lane & 15, fq = lane >> 4;
;     const int K = g.K, nt = K / BK;
;     unsigned voffA[2], voffB[2];
; #pragma unroll
;     for (int i = 0; i < 2; ++i) { int R, C; stage_rc(tid * 16 + i * 8192, R, C); const int Rb = Epi::PERM ? ((R & ~31) + perm32(R & 31)) : R;
;         voffA[i] = (unsigned)(R * K + C) * 2u; voffB[i] = (unsigned)(Rb * K + C) * 2u; }
;     const size_t kstep = (size_t)(BK * 2);
;     const size_t hstep = (size_t)HALF * K * 2;
;     const size_t tstep = 2 * hstep;
;     const unsigned ldsw = (unsigned)wid * 1024u;
;     const int aoff = lds_byte(wr * 64 + fr, fq * 8), boff = lds_byte(wc * 32 + fr, fq * 8);
;     ...
;     Unit cur, nxt; int ui = 0;
;     if (!S.next(0, cur)) return;
;     f32x4 acc[2][2][4][2];
; #pragma unroll
;     for (int a = 0; a < 2; ++a)
; #pragma unroll
;         for (int b = 0; b < 2; ++b)
; #pragma unroll
;             for (int m = 0; m < 4; ++m)
; #pragma unroll
;                 for (int n = 0; n < 2; ++n) acc[a][b][m][n] = (f32x4){0.f, 0.f, 0.f, 0.f};
;     bf16x8 At[4][2], B0[2][2], B1[2][2];
;     const char* cA = (const char*)g.A + (size_t)cur.pm * tstep; const char* cB = (const char*)g.Bt + (size_t)cur.pn * tstep;
;     PG8_STAGEB(PG8_SB(0, 0), cB); PG8_STAGE(PG8_SA(0, 0), cA); PG8_STAGEB(PG8_SB(0, 1), cB + hstep); PG8_STAGE(PG8_SA(0, 1), cA + hstep);
;     if (wr == 1) PG8_BAR;
;     PG8_WAIT_V(4); PG8_BAR;
;     PG8_STAGEB(PG8_SB(1, 0), cB + kstep); PG8_STAGE(PG8_SA(1, 0), cA + kstep); PG8_STAGEB(PG8_SB(1, 1), cB + hstep + kstep);
;     PG8_WAIT_V(6); PG8_BAR;
.LBB0_418:
	s_or_b64 exec, exec, s[0:1]
	v_readlane_b32 s0, v254, 13
	s_mov_b64 s[6:7], s[94:95]
	v_mov_b32_e32 v10, v250
	v_readlane_b32 s1, v254, 14
	s_waitcnt lgkmcnt(0)
	s_barrier
	s_andn2_b64 vcc, exec, s[0:1]
	v_readfirstlane_b32 s50, v10
	s_cbranch_vccnz .LBB0_470
	v_lshlrev_b32_e32 v0, 4, v10
	v_add_u32_e32 v2, 0x2000, v0
	v_ashrrev_i32_e32 v3, 31, v2
	v_lshrrev_b32_e32 v3, 22, v3
	v_add_u32_e32 v3, v2, v3
	v_ashrrev_i32_e32 v11, 10, v3
	v_mul_i32_i24_e32 v3, 0x400, v11
	v_sub_u32_e32 v2, v2, v3
	v_lshrrev_b32_e32 v3, 4, v2
	v_bitop3_b32 v2, v3, v2, 32 bitop3:0x6c
	v_ashrrev_i32_e32 v3, 31, v2
	v_lshrrev_b32_e32 v3, 26, v3
	v_add_u32_e32 v3, v2, v3
	v_lshlrev_b32_e32 v4, 3, v11
	v_ashrrev_i32_e32 v12, 6, v3
	v_and_b32_e32 v4, -16, v4
	v_add_u32_e32 v4, v12, v4
	v_and_b32_e32 v5, 3, v12
	s_mov_b32 s4, 0xfffe0
	v_lshrrev_b32_e32 v6, 2, v4
	v_lshlrev_b32_e32 v7, 1, v4
	v_and_or_b32 v5, v4, s4, v5
	v_and_b32_e32 v6, 4, v6
	v_and_b32_e32 v7, 24, v7
	v_and_b32_e32 v3, 0xc0, v3
	v_or3_b32 v5, v5, v6, v7
	v_sub_u32_e32 v2, v2, v3
	v_mov_b32_e32 v7, 1
	v_lshlrev_b32_e32 v6, 5, v11
	v_ashrrev_i16_sdwa v2, v7, sext(v2) dst_sel:DWORD dst_unused:UNUSED_PAD src0_sel:DWORD src1_sel:BYTE_0
	v_and_b32_e32 v6, 32, v6
	v_bfe_i32 v13, v2, 0, 16
	v_add_lshl_u32 v2, v6, v13, 1
	v_lshl_add_u32 v156, v5, 12, v2
	v_lshl_add_u32 v158, v4, 12, v2
	v_bfe_i32 v2, v10, 27, 1
	v_lshrrev_b32_e32 v2, 22, v2
	v_add_u32_e32 v2, v0, v2
	v_and_b32_e32 v2, 0xfffffc00, v2
	v_sub_u32_e32 v0, v0, v2
	v_lshrrev_b32_e32 v2, 4, v0
	v_bitop3_b32 v2, v2, v0, 32 bitop3:0x6c
	v_ashrrev_i32_e32 v0, 31, v0
	v_lshrrev_b32_e32 v0, 26, v0
	v_add_u32_e32 v0, v2, v0
	v_ashrrev_i32_e32 v14, 6, v0
	v_ashrrev_i32_e32 v0, 31, v10
	v_lshrrev_b32_e32 v0, 26, v0
	s_load_dwordx2 s[0:1], s[6:7], 0xf0
	v_add_u32_e32 v0, v10, v0
	v_ashrrev_i32_e32 v15, 6, v0
	v_lshlrev_b32_e32 v0, 3, v15
	v_and_b32_e32 v0, -16, v0
	v_add_u32_e32 v3, v14, v0
	v_readlane_b32 s20, v255, 46
	s_waitcnt lgkmcnt(0)
	s_add_u32 s51, s0, 0x15b00000
	v_and_b32_e32 v0, 3, v14
	v_lshrrev_b32_e32 v4, 2, v3
	v_lshlrev_b32_e32 v5, 1, v3
	s_mov_b32 s38, s20
	s_mul_i32 s20, s20, 0x4500000
	s_addc_u32 s52, s1, 0
	v_and_or_b32 v0, v3, s4, v0
	v_and_b32_e32 v4, 4, v4
	v_and_b32_e32 v5, 24, v5
	s_add_u32 s53, s0, s20
	v_or3_b32 v0, v0, v4, v5
	v_mul_i32_i24_e32 v5, 64, v14
	v_readlane_b32 s21, v255, 47
	s_addc_u32 s54, s1, 0
	s_ashr_i32 s24, s50, 6
	v_sub_u32_e32 v2, v2, v5
	s_ashr_i32 s25, s50, 8
	s_lshl_b32 s55, s24, 10
	v_lshlrev_b32_e32 v4, 5, v15
	v_ashrrev_i16_sdwa v2, v7, sext(v2) dst_sel:DWORD dst_unused:UNUSED_PAD src0_sel:DWORD src1_sel:BYTE_0
	v_readlane_b32 s20, v254, 40
	v_and_b32_e32 v4, 32, v4
	v_bfe_i32 v16, v2, 0, 16
	v_readlane_b32 s21, v254, 41
	s_add_u32 s20, s53, s20
	v_add_lshl_u32 v2, v4, v16, 1
	s_addc_u32 s21, s54, s21
	s_add_i32 s62, s55, 0
	v_lshl_add_u32 v0, v0, 12, v2
	s_add_i32 m0, s62, 0x10000
	v_readlane_b32 s30, v254, 56
	global_load_lds_dwordx4 v0, s[20:21]
	s_add_i32 m0, s62, 0x12000
	v_readlane_b32 s31, v254, 57
	s_add_u32 s30, s51, s30
	v_lshl_add_u32 v160, v3, 12, v2
	global_load_lds_dwordx4 v156, s[20:21]
	s_addc_u32 s31, s52, s31
	s_mov_b32 m0, s62
	s_add_i32 s63, s62, 0x2000
	global_load_lds_dwordx4 v160, s[30:31]
	s_mov_b32 m0, s63
	s_add_u32 s34, s20, 0x80000
	global_load_lds_dwordx4 v158, s[30:31]
	s_addc_u32 s35, s21, 0
	s_add_i32 m0, s62, 0x14000
	s_load_dwordx2 s[6:7], s[6:7], 0xd8
	global_load_lds_dwordx4 v0, s[34:35]
	s_add_i32 m0, s62, 0x16000
	v_mov_b32_e32 v157, v1
	global_load_lds_dwordx4 v156, s[34:35]
	s_add_u32 s34, s30, 0x80000
	s_addc_u32 s35, s31, 0
	s_add_i32 s66, s62, 0x4000
	s_mov_b32 m0, s66
	s_add_i32 s67, s62, 0x6000
	global_load_lds_dwordx4 v160, s[34:35]
	s_mov_b32 m0, s67
	v_mov_b32_e32 v161, v1
	global_load_lds_dwordx4 v158, s[34:35]
	v_mov_b32_e32 v159, v1
	v_lshl_add_u64 v[8:9], s[20:21], 0, v[0:1]
	v_lshl_add_u64 v[6:7], s[20:21], 0, v[156:157]
	v_lshl_add_u64 v[4:5], s[30:31], 0, v[160:161]
	s_add_i32 m0, s62, 0x17f80
	s_nop 0
	global_load_lds_dwordx4 v0, s[20:21] offset:128
	s_add_i32 m0, s62, 0x19f80
	s_nop 0
	global_load_lds_dwordx4 v156, s[20:21] offset:128
	s_add_i32 m0, s62, 0x7f80
	s_nop 0
	global_load_lds_dwordx4 v160, s[30:31] offset:128
	s_add_i32 m0, s62, 0x9f80
	s_nop 0
	global_load_lds_dwordx4 v158, s[30:31] offset:128
	s_add_u32 s100, s20, 0x80080
	s_addc_u32 s101, s21, 0
	s_add_i32 m0, s62, 0x1c000
	s_nop 0
	global_load_lds_dwordx4 v0, s[100:101]
	s_add_i32 m0, s62, 0x1e000
	s_nop 0
	global_load_lds_dwordx4 v156, s[100:101]
	s_cmp_lg_u32 s25, 1
	v_lshl_add_u64 v[2:3], s[30:31], 0, v[158:159]
	s_cbranch_scc1 .LBB0_421
	s_barrier
.LBB0_421:
	s_lshl_b32 s38, s38, 13
	s_add_u32 s0, s0, 0x17b00000
	s_addc_u32 s1, s1, 0
	s_lshl_b64 s[34:35], s[38:39], 2
	s_waitcnt lgkmcnt(0)
	s_add_u32 s6, s6, s34
	s_addc_u32 s7, s7, s35
	s_lshl_b32 s24, s24, 12
	s_add_i32 m0, s62, 0x18000
	v_lshl_add_u64 v[8:9], v[8:9], 0, s[16:17]
	s_lshl_b32 s34, s25, 13
	s_and_b32 s35, s24, 0x3000
	s_waitcnt vmcnt(10)
	s_barrier
	v_lshl_add_u64 v[6:7], v[6:7], 0, s[16:17]
	s_add_i32 m0, s62, 0x1a000
	s_add_i32 s38, s62, 0x8000
	s_add_i32 s80, s62, 0xa000
	v_lshl_add_u64 v[4:5], v[4:5], 0, s[16:17]
	s_mov_b32 m0, s38
	s_add_u32 s24, s20, 0x80080
	v_lshl_add_u64 v[2:3], v[2:3], 0, s[16:17]
	s_mov_b32 m0, s80
	s_addc_u32 s25, s21, 0
	s_add_i32 m0, s62, 0x1c000
	v_lshl_add_u64 v[2:3], s[24:25], 0, v[0:1]
	v_lshl_add_u64 v[2:3], s[24:25], 0, v[156:157]
	s_add_i32 m0, s62, 0x1e000
	v_lshlrev_b32_e32 v5, 2, v10
	v_and_b32_e32 v2, 15, v10
	v_and_b32_e32 v3, 48, v10
	v_lshlrev_b32_e32 v2, 6, v2
	v_and_b32_e32 v5, 32, v5
	v_or_b32_e32 v4, v2, v3
	v_bitop3_b32 v2, v2, v5, v3 bitop3:0x36
	v_or_b32_e32 v170, s35, v2
	v_lshlrev_b32_e32 v2, 15, v15
	v_and_b32_e32 v2, 0xffff0000, v2
	v_bitop3_b32 v3, v4, s34, v5 bitop3:0xde
	v_lshl_add_u32 v2, v14, 12, v2
	v_and_b32_e32 v4, 1, v15
	v_lshl_or_b32 v2, v4, 6, v2
	v_lshl_add_u32 v162, v16, 1, v2
	v_lshlrev_b32_e32 v2, 15, v11
	v_and_b32_e32 v2, 0xffff0000, v2
	s_waitcnt vmcnt(6)
	v_lshl_add_u32 v2, v12, 12, v2
	v_and_b32_e32 v4, 1, v11
	v_lshl_or_b32 v2, v4, 6, v2
	v_readlane_b32 s24, v254, 54
	v_mov_b32_e32 v163, v1
	v_lshl_add_u32 v164, v13, 1, v2
	v_mov_b32_e32 v165, v1
	s_mov_b32 s81, 0
	v_add_u32_e32 v171, 0, v3
	v_readlane_b32 s82, v254, 39
	s_mov_b32 s83, s24
	s_barrier
	v_readlane_b32 s25, v254, 55
	s_branch .LBB0_423
